# v16 + sw_layers (P0b): the 20 shift-vector loads per weight row issued together with one wait instead of a pair-at-a-time ladder
# speedup vs baseline: 1.0099x; 1.0099x over previous
; __device__ __forceinline__ void sw_layers(const Args& a, int l_lo, int l_hi, int wb, int nwb) {
;     ...
;         for (int u = 0; u < 2; ++u) {
;             float acc[5] = {0.f, 0.f, 0.f, 0.f, 0.f};
; #pragma unroll
;             for (int hseg = 0; hseg < 2; ++hseg) {
;                 const int k0 = hseg * 512 + 8 * lane;
;                 float wf[8]; unpack8(wv[u][hseg], wf);
; #pragma unroll
;                 for (int bb = 0; bb < 5; ++bb) {
;                     const f32x4 s0 = *(const f32x4*)(shp[u] + (size_t)bb * NMODC + k0), s1 = *(const f32x4*)(shp[u] + (size_t)bb * NMODC + k0 + 4);
;                     acc[bb] += s0[0] * wf[0] + s0[1] * wf[1] + s0[2] * wf[2] + s0[3] * wf[3] + s1[0] * wf[4] + s1[1] * wf[5] + s1[2] * wf[6] + s1[3] * wf[7];
;                 }
;             }
.LBB0_94:
	s_or_b64 exec, exec, s[40:41]
	v_readlane_b32 s8, v251, 0
	v_mul_hi_i32_i24_e32 v29, 0x1e000, v30
	v_mul_i32_i24_e32 v28, 0x1e000, v30
	v_readlane_b32 s22, v251, 14
	v_readlane_b32 s23, v251, 15
	v_mov_b32_e32 v23, 0x3000
	v_cndmask_b32_e64 v206, v23, 0, s[0:1]
	v_lshl_add_u64 v[28:29], s[22:23], 0, v[28:29]
	v_lshl_add_u64 v[28:29], v[28:29], 0, v[206:207]
	v_lshlrev_b32_e32 v206, 2, v18
	s_waitcnt vmcnt(0)
	v_lshlrev_b32_e32 v23, 16, v14
	v_and_b32_e32 v45, 0xffff0000, v14
	v_lshlrev_b32_e32 v54, 16, v15
	v_and_b32_e32 v55, 0xffff0000, v15
	v_lshl_add_u64 v[14:15], v[28:29], 0, v[206:207]
	s_mov_b64 s[98:99], 0x6000
	v_lshl_add_u64 v[88:89], v[14:15], 0, s[98:99]
	s_mov_b64 s[98:99], 0xc000
	v_lshl_add_u64 v[90:91], v[14:15], 0, s[98:99]
	s_mov_b64 s[98:99], 0x12000
	v_lshl_add_u64 v[92:93], v[14:15], 0, s[98:99]
	s_mov_b64 s[98:99], 0x18000
	v_lshl_add_u64 v[94:95], v[14:15], 0, s[98:99]
	global_load_dwordx4 v[96:99], v[14:15], off
	global_load_dwordx4 v[100:103], v[14:15], off offset:16
	global_load_dwordx4 v[104:107], v[14:15], off offset:2048
	global_load_dwordx4 v[108:111], v[14:15], off offset:2064
	global_load_dwordx4 v[112:115], v[88:89], off
	global_load_dwordx4 v[116:119], v[88:89], off offset:16
	global_load_dwordx4 v[120:123], v[88:89], off offset:2048
	global_load_dwordx4 v[124:127], v[88:89], off offset:2064
	global_load_dwordx4 v[128:131], v[90:91], off
	global_load_dwordx4 v[132:135], v[90:91], off offset:16
	global_load_dwordx4 v[136:139], v[90:91], off offset:2048
	global_load_dwordx4 v[140:143], v[90:91], off offset:2064
	global_load_dwordx4 v[144:147], v[92:93], off
	global_load_dwordx4 v[148:151], v[92:93], off offset:16
	global_load_dwordx4 v[152:155], v[92:93], off offset:2048
	global_load_dwordx4 v[156:159], v[92:93], off offset:2064
	global_load_dwordx4 v[160:163], v[94:95], off
	global_load_dwordx4 v[164:167], v[94:95], off offset:16
	global_load_dwordx4 v[168:171], v[94:95], off offset:2048
	global_load_dwordx4 v[172:175], v[94:95], off offset:2064
	s_waitcnt vmcnt(0)
	s_nop 0
	s_nop 0
	v_lshlrev_b32_e32 v56, 16, v16
	v_and_b32_e32 v57, 0xffff0000, v16
	v_lshlrev_b32_e32 v58, 16, v17
	v_and_b32_e32 v59, 0xffff0000, v17
	s_mov_b64 s[0:1], 0x6000
	s_waitcnt vmcnt(4)
	v_and_b32_e32 v64, 0xffff0000, v13
	s_mov_b64 s[40:41], -1
	v_readlane_b32 s9, v251, 1
	v_readlane_b32 s10, v251, 2
	v_readlane_b32 s11, v251, 3
	v_readlane_b32 s12, v251, 4
	v_readlane_b32 s13, v251, 5
	v_readlane_b32 s14, v251, 6
	v_readlane_b32 s15, v251, 7
	v_readlane_b32 s16, v251, 8
	v_readlane_b32 s17, v251, 9
	v_readlane_b32 s18, v251, 10
	v_readlane_b32 s19, v251, 11
	v_readlane_b32 s20, v251, 12
	v_readlane_b32 s21, v251, 13
	s_waitcnt vmcnt(0)
	v_mul_f32_e32 v16, v97, v45
	v_fmac_f32_e32 v16, v96, v23
	v_fmac_f32_e32 v16, v98, v54
	v_fmac_f32_e32 v16, v99, v55
	v_fmac_f32_e32 v16, v100, v56
	v_fmac_f32_e32 v16, v101, v57
	v_fmac_f32_e32 v16, v102, v58
	v_fmac_f32_e32 v16, v103, v59
	v_add_f32_e32 v60, 0, v16
	v_lshl_add_u64 v[16:17], v[14:15], 0, s[0:1]
	v_add_co_u32_e64 v30, s[0:1], s7, v14
	s_nop 1
	v_addc_co_u32_e64 v31, s[0:1], 0, v15, s[0:1]
	s_nop 0
	s_nop 0
	s_mov_b64 s[0:1], 0xc000
	v_lshl_add_u64 v[28:29], v[14:15], 0, s[0:1]
	s_mov_b32 s0, 0xc000
	s_waitcnt vmcnt(1)
	v_mul_f32_e32 v16, v113, v45
	v_fmac_f32_e32 v16, v112, v23
	v_fmac_f32_e32 v16, v114, v54
	v_fmac_f32_e32 v16, v115, v55
	s_waitcnt vmcnt(0)
	v_fmac_f32_e32 v16, v116, v56
	v_fmac_f32_e32 v16, v117, v57
	v_fmac_f32_e32 v16, v118, v58
	v_fmac_f32_e32 v16, v119, v59
	v_add_f32_e32 v61, 0, v16
	v_add_co_u32_e64 v16, s[0:1], s0, v14
	s_nop 1
	v_addc_co_u32_e64 v17, s[0:1], 0, v15, s[0:1]
	s_nop 0
	s_nop 0
	s_mov_b64 s[0:1], 0x12000
	v_lshl_add_u64 v[32:33], v[14:15], 0, s[0:1]
	s_mov_b32 s0, 0x12000
	s_waitcnt vmcnt(1)
	v_mul_f32_e32 v28, v129, v45
	v_fmac_f32_e32 v28, v128, v23
	v_fmac_f32_e32 v28, v130, v54
	v_fmac_f32_e32 v28, v131, v55
	s_waitcnt vmcnt(0)
	v_fmac_f32_e32 v28, v132, v56
	v_fmac_f32_e32 v28, v133, v57
	v_fmac_f32_e32 v28, v134, v58
	v_fmac_f32_e32 v28, v135, v59
	v_add_f32_e32 v62, 0, v28
	v_add_co_u32_e64 v28, s[0:1], s0, v14
	s_nop 1
	v_addc_co_u32_e64 v29, s[0:1], 0, v15, s[0:1]
	s_nop 0
	s_nop 0
	s_mov_b64 s[0:1], 0x18000
	s_waitcnt vmcnt(1)
	v_mul_f32_e32 v32, v145, v45
	v_fmac_f32_e32 v32, v144, v23
	v_fmac_f32_e32 v32, v146, v54
	v_fmac_f32_e32 v32, v147, v55
	s_waitcnt vmcnt(0)
	v_fmac_f32_e32 v32, v148, v56
	v_fmac_f32_e32 v32, v149, v57
	v_fmac_f32_e32 v32, v150, v58
	v_fmac_f32_e32 v32, v151, v59
	v_lshl_add_u64 v[50:51], v[14:15], 0, s[0:1]
	s_mov_b32 s0, 0x18000
	v_add_f32_e32 v63, 0, v32
	v_add_co_u32_e64 v32, s[0:1], s0, v14
	s_nop 1
	v_addc_co_u32_e64 v33, s[0:1], 0, v15, s[0:1]
	s_nop 0
	s_nop 0
	s_nop 0
	s_mov_b64 s[0:1], 0x6800
	s_waitcnt vmcnt(1)
	v_mul_f32_e32 v45, v161, v45
	v_fmac_f32_e32 v45, v160, v23
	v_fmac_f32_e32 v45, v162, v54
	v_fmac_f32_e32 v45, v163, v55
	s_waitcnt vmcnt(0)
	v_fmac_f32_e32 v45, v164, v56
	v_fmac_f32_e32 v45, v165, v57
	v_fmac_f32_e32 v45, v166, v58
	v_fmac_f32_e32 v45, v167, v59
	v_add_f32_e32 v23, 0, v45
	v_lshlrev_b32_e32 v45, 16, v10
	v_and_b32_e32 v54, 0xffff0000, v10
	v_lshlrev_b32_e32 v55, 16, v11
	v_and_b32_e32 v56, 0xffff0000, v11
	v_lshlrev_b32_e32 v57, 16, v12
	v_and_b32_e32 v58, 0xffff0000, v12
	v_lshlrev_b32_e32 v59, 16, v13
	s_nop 0
	s_nop 0
	s_waitcnt vmcnt(0)
	v_mul_f32_e32 v47, v105, v54
	v_fmac_f32_e32 v47, v104, v45
	v_fmac_f32_e32 v47, v106, v55
	v_fmac_f32_e32 v47, v107, v56
	v_fmac_f32_e32 v47, v108, v57
	v_fmac_f32_e32 v47, v109, v58
	v_fmac_f32_e32 v47, v110, v59
	v_fmac_f32_e32 v47, v111, v64
	v_add_f32_e32 v10, v60, v47
	v_lshl_add_u64 v[12:13], v[14:15], 0, s[0:1]
	s_nop 0
	s_nop 0
	s_mov_b64 s[0:1], 0xc800
	v_lshl_add_u64 v[30:31], v[14:15], 0, s[0:1]
	s_mov_b64 s[0:1], 0x12800
	s_waitcnt vmcnt(1)
; __device__ __forceinline__ void sw_layers(const Args& a, int l_lo, int l_hi, int wb, int nwb) {
;     ...
;             for (int hseg = 0; hseg < 2; ++hseg) {
;                 const int k0 = hseg * 512 + 8 * lane;
;                 float wf[8]; unpack8(wv[u][hseg], wf);
; #pragma unroll
;                 for (int bb = 0; bb < 5; ++bb) {
;                     const f32x4 s0 = *(const f32x4*)(shp[u] + (size_t)bb * NMODC + k0), s1 = *(const f32x4*)(shp[u] + (size_t)bb * NMODC + k0 + 4);
;                     acc[bb] += s0[0] * wf[0] + s0[1] * wf[1] + s0[2] * wf[2] + s0[3] * wf[3] + s1[0] * wf[4] + s1[1] * wf[5] + s1[2] * wf[6] + s1[3] * wf[7];
;                 }
;             }
; #pragma unroll
;             for (int bb = 0; bb < 5; ++bb) acc[bb] = wave_sum(acc[bb]);
;             if (lane == 0 && okp[u]) {
; #pragma unroll
;                 for (int bb = 0; bb < 5; ++bb) dstp[u][(size_t)bb * ldp[u]] = acc[bb];
;             }
	v_mul_f32_e32 v11, v121, v54
	v_fmac_f32_e32 v11, v120, v45
	v_fmac_f32_e32 v11, v122, v55
	v_fmac_f32_e32 v11, v123, v56
	s_waitcnt vmcnt(0)
	v_fmac_f32_e32 v11, v124, v57
	v_fmac_f32_e32 v11, v125, v58
	v_fmac_f32_e32 v11, v126, v59
	v_fmac_f32_e32 v11, v127, v64
	s_nop 0
	s_nop 0
	v_add_f32_e32 v12, v61, v11
	v_lshl_add_u64 v[16:17], v[14:15], 0, s[0:1]
	s_mov_b64 s[0:1], 0x18800
	s_waitcnt vmcnt(1)
	v_mul_f32_e32 v11, v137, v54
	v_fmac_f32_e32 v11, v136, v45
	v_fmac_f32_e32 v11, v138, v55
	v_fmac_f32_e32 v11, v139, v56
	s_nop 0
	s_nop 0
	s_nop 0
	s_waitcnt vmcnt(2)
	v_fmac_f32_e32 v11, v140, v57
	v_fmac_f32_e32 v11, v141, v58
	v_fmac_f32_e32 v11, v142, v59
	v_fmac_f32_e32 v11, v143, v64
	v_add_f32_e32 v11, v62, v11
	s_waitcnt vmcnt(1)
	v_mul_f32_e32 v13, v153, v54
	v_fmac_f32_e32 v13, v152, v45
	v_fmac_f32_e32 v13, v154, v55
	v_lshl_add_u64 v[28:29], v[14:15], 0, s[0:1]
	v_fmac_f32_e32 v13, v155, v56
	s_nop 0
	s_nop 0
	s_nop 0
	s_waitcnt vmcnt(2)
	v_fmac_f32_e32 v13, v156, v57
	v_fmac_f32_e32 v13, v157, v58
	v_fmac_f32_e32 v13, v158, v59
	v_fmac_f32_e32 v13, v159, v64
	v_add_f32_e32 v13, v63, v13
	s_waitcnt vmcnt(1)
	v_mul_f32_e32 v15, v169, v54
	v_fmac_f32_e32 v15, v168, v45
	v_fmac_f32_e32 v15, v170, v55
	v_fmac_f32_e32 v15, v171, v56
	s_waitcnt vmcnt(0)
	v_fmac_f32_e32 v15, v172, v57
	v_fmac_f32_e32 v15, v173, v58
	v_fmac_f32_e32 v15, v174, v59
	v_fmac_f32_e32 v15, v175, v64
	v_add_f32_e32 v14, v23, v15
	ds_bpermute_b32 v15, v39, v10
	ds_bpermute_b32 v16, v39, v12
	ds_bpermute_b32 v17, v39, v11
	ds_bpermute_b32 v23, v39, v13
	ds_bpermute_b32 v28, v39, v14
	s_waitcnt lgkmcnt(4)
	v_add_f32_e32 v10, v10, v15
	s_waitcnt lgkmcnt(3)
	v_add_f32_e32 v12, v12, v16
	s_waitcnt lgkmcnt(2)
	v_add_f32_e32 v11, v11, v17
	s_waitcnt lgkmcnt(1)
	v_add_f32_e32 v13, v13, v23
	s_waitcnt lgkmcnt(0)
	v_add_f32_e32 v14, v14, v28
	ds_bpermute_b32 v15, v40, v10
	ds_bpermute_b32 v16, v40, v12
	ds_bpermute_b32 v17, v40, v11
	ds_bpermute_b32 v23, v40, v13
	ds_bpermute_b32 v28, v40, v14
	s_waitcnt lgkmcnt(4)
	v_add_f32_e32 v10, v10, v15
	s_waitcnt lgkmcnt(3)
	v_add_f32_e32 v12, v12, v16
	s_waitcnt lgkmcnt(2)
	v_add_f32_e32 v11, v11, v17
	s_waitcnt lgkmcnt(1)
	v_add_f32_e32 v13, v13, v23
	s_waitcnt lgkmcnt(0)
	v_add_f32_e32 v14, v14, v28
	ds_bpermute_b32 v15, v41, v10
	ds_bpermute_b32 v16, v41, v12
	ds_bpermute_b32 v17, v41, v11
	ds_bpermute_b32 v23, v41, v13
	ds_bpermute_b32 v28, v41, v14
	s_waitcnt lgkmcnt(4)
	v_add_f32_e32 v10, v10, v15
	s_waitcnt lgkmcnt(3)
	v_add_f32_e32 v12, v12, v16
	s_waitcnt lgkmcnt(2)
	v_add_f32_e32 v11, v11, v17
	s_waitcnt lgkmcnt(1)
	v_add_f32_e32 v13, v13, v23
	s_waitcnt lgkmcnt(0)
	v_add_f32_e32 v14, v14, v28
	ds_bpermute_b32 v15, v42, v10
	ds_bpermute_b32 v16, v42, v12
	ds_bpermute_b32 v17, v42, v11
	ds_bpermute_b32 v23, v42, v13
	ds_bpermute_b32 v28, v42, v14
	s_waitcnt lgkmcnt(4)
	v_add_f32_e32 v10, v10, v15
	s_waitcnt lgkmcnt(3)
	v_add_f32_e32 v12, v12, v16
	s_waitcnt lgkmcnt(2)
	v_add_f32_e32 v11, v11, v17
	s_waitcnt lgkmcnt(1)
	v_add_f32_e32 v13, v13, v23
	s_waitcnt lgkmcnt(0)
	v_add_f32_e32 v14, v14, v28
	ds_bpermute_b32 v15, v43, v10
	ds_bpermute_b32 v16, v43, v12
	ds_bpermute_b32 v17, v43, v11
	ds_bpermute_b32 v23, v43, v13
	ds_bpermute_b32 v28, v43, v14
	s_waitcnt lgkmcnt(4)
	v_add_f32_e32 v10, v10, v15
	s_waitcnt lgkmcnt(3)
	v_add_f32_e32 v12, v12, v16
	s_waitcnt lgkmcnt(2)
	v_add_f32_e32 v11, v11, v17
	s_waitcnt lgkmcnt(1)
	v_add_f32_e32 v13, v13, v23
	s_waitcnt lgkmcnt(0)
	v_add_f32_e32 v14, v14, v28
	ds_bpermute_b32 v15, v44, v10
	ds_bpermute_b32 v16, v44, v12
	ds_bpermute_b32 v17, v44, v11
	ds_bpermute_b32 v23, v44, v13
	ds_bpermute_b32 v28, v44, v14
	s_and_saveexec_b64 s[0:1], vcc
	s_cbranch_execz .LBB0_96
	s_waitcnt lgkmcnt(4)
	v_add_f32_e32 v10, v10, v15
	s_waitcnt lgkmcnt(2)
	v_add_f32_e32 v17, v11, v17
	global_store_dword v[24:25], v10, off
	v_lshlrev_b32_e32 v10, 2, v26
	v_mov_b32_e32 v11, v207
	s_waitcnt lgkmcnt(1)
	v_add_f32_e32 v23, v13, v23
	v_add_f32_e32 v16, v12, v16
	v_lshl_add_u64 v[12:13], v[24:25], 0, v[10:11]
	global_store_dword v[12:13], v16, off
	v_lshl_add_u64 v[12:13], v[12:13], 0, v[10:11]
	global_store_dword v[12:13], v17, off
	v_lshl_add_u64 v[12:13], v[12:13], 0, v[10:11]
	s_waitcnt lgkmcnt(0)
	v_add_f32_e32 v14, v14, v28
	v_lshl_add_u64 v[10:11], v[12:13], 0, v[10:11]
	s_orn2_b64 s[40:41], s[38:39], exec
	global_store_dword v[12:13], v23, off
	global_store_dword v[10:11], v14, off
; __device__ __forceinline__ void sw_layers(const Args& a, int l_lo, int l_hi, int wb, int nwb) {
;     ...
;         for (int u = 0; u < 2; ++u) {
;             float acc[5] = {0.f, 0.f, 0.f, 0.f, 0.f};
; #pragma unroll
;             for (int hseg = 0; hseg < 2; ++hseg) {
;                 const int k0 = hseg * 512 + 8 * lane;
;                 float wf[8]; unpack8(wv[u][hseg], wf);
; #pragma unroll
;                 for (int bb = 0; bb < 5; ++bb) {
;                     const f32x4 s0 = *(const f32x4*)(shp[u] + (size_t)bb * NMODC + k0), s1 = *(const f32x4*)(shp[u] + (size_t)bb * NMODC + k0 + 4);
;                     acc[bb] += s0[0] * wf[0] + s0[1] * wf[1] + s0[2] * wf[2] + s0[3] * wf[3] + s1[0] * wf[4] + s1[1] * wf[5] + s1[2] * wf[6] + s1[3] * wf[7];
;                 }
;             }
.LBB0_96:
	s_or_b64 exec, exec, s[0:1]
	v_readlane_b32 s8, v251, 0
	v_mul_hi_i32_i24_e32 v11, 0x1e000, v27
	v_mul_i32_i24_e32 v10, 0x1e000, v27
	v_readlane_b32 s22, v251, 14
	v_readlane_b32 s23, v251, 15
	v_mov_b32_e32 v12, 0x3000
	v_cndmask_b32_e64 v12, v12, 0, s[36:37]
	v_lshl_add_u64 v[10:11], s[22:23], 0, v[10:11]
	v_mov_b32_e32 v13, v207
	v_lshl_add_u64 v[10:11], v[10:11], 0, v[12:13]
	s_waitcnt lgkmcnt(1)
	v_lshlrev_b32_e32 v23, 16, v6
	v_and_b32_e32 v32, 0xffff0000, v6
	v_lshlrev_b32_e32 v33, 16, v7
	v_and_b32_e32 v45, 0xffff0000, v7
	v_lshl_add_u64 v[6:7], v[10:11], 0, v[206:207]
	s_mov_b64 s[98:99], 0x6000
	v_lshl_add_u64 v[88:89], v[6:7], 0, s[98:99]
	s_mov_b64 s[98:99], 0xc000
	v_lshl_add_u64 v[90:91], v[6:7], 0, s[98:99]
	s_mov_b64 s[98:99], 0x12000
	v_lshl_add_u64 v[92:93], v[6:7], 0, s[98:99]
	s_mov_b64 s[98:99], 0x18000
	v_lshl_add_u64 v[94:95], v[6:7], 0, s[98:99]
	global_load_dwordx4 v[96:99], v[6:7], off
	global_load_dwordx4 v[100:103], v[6:7], off offset:16
	global_load_dwordx4 v[104:107], v[6:7], off offset:2048
	global_load_dwordx4 v[108:111], v[6:7], off offset:2064
	global_load_dwordx4 v[112:115], v[88:89], off
	global_load_dwordx4 v[116:119], v[88:89], off offset:16
	global_load_dwordx4 v[120:123], v[88:89], off offset:2048
	global_load_dwordx4 v[124:127], v[88:89], off offset:2064
	global_load_dwordx4 v[128:131], v[90:91], off
	global_load_dwordx4 v[132:135], v[90:91], off offset:16
	global_load_dwordx4 v[136:139], v[90:91], off offset:2048
	global_load_dwordx4 v[140:143], v[90:91], off offset:2064
	global_load_dwordx4 v[144:147], v[92:93], off
	global_load_dwordx4 v[148:151], v[92:93], off offset:16
	global_load_dwordx4 v[152:155], v[92:93], off offset:2048
	global_load_dwordx4 v[156:159], v[92:93], off offset:2064
	global_load_dwordx4 v[160:163], v[94:95], off
	global_load_dwordx4 v[164:167], v[94:95], off offset:16
	global_load_dwordx4 v[168:171], v[94:95], off offset:2048
	global_load_dwordx4 v[172:175], v[94:95], off offset:2064
	s_waitcnt vmcnt(0)
	v_lshlrev_b32_e32 v46, 16, v8
	v_and_b32_e32 v47, 0xffff0000, v8
	v_lshlrev_b32_e32 v48, 16, v9
	v_and_b32_e32 v49, 0xffff0000, v9
	s_nop 0
	s_nop 0
	s_mov_b64 s[0:1], 0x6000
	s_xor_b64 s[38:39], s[40:41], -1
	v_readlane_b32 s9, v251, 1
	v_readlane_b32 s10, v251, 2
	v_readlane_b32 s11, v251, 3
	v_readlane_b32 s12, v251, 4
	v_readlane_b32 s13, v251, 5
	v_readlane_b32 s14, v251, 6
	v_readlane_b32 s15, v251, 7
	v_readlane_b32 s16, v251, 8
	v_readlane_b32 s17, v251, 9
	v_readlane_b32 s18, v251, 10
	v_readlane_b32 s19, v251, 11
	v_readlane_b32 s20, v251, 12
	v_readlane_b32 s21, v251, 13
	s_waitcnt vmcnt(0)
	v_mul_f32_e32 v13, v97, v32
	v_fmac_f32_e32 v13, v96, v23
	v_fmac_f32_e32 v13, v98, v33
	v_fmac_f32_e32 v13, v99, v45
	v_fmac_f32_e32 v13, v100, v46
	v_fmac_f32_e32 v13, v101, v47
	v_fmac_f32_e32 v13, v102, v48
	v_fmac_f32_e32 v13, v103, v49
	v_lshl_add_u64 v[14:15], v[6:7], 0, s[0:1]
	v_add_co_u32_e64 v12, s[0:1], s7, v6
	v_add_f32_e32 v50, 0, v13
	s_nop 0
	v_addc_co_u32_e64 v13, s[0:1], 0, v7, s[0:1]
	s_nop 0
	s_nop 0
	s_nop 0
	s_mov_b64 s[0:1], 0xc000
	s_waitcnt vmcnt(1)
	v_mul_f32_e32 v9, v113, v32
	v_fmac_f32_e32 v9, v112, v23
	v_fmac_f32_e32 v9, v114, v33
	v_fmac_f32_e32 v9, v115, v45
	s_waitcnt vmcnt(0)
	v_fmac_f32_e32 v9, v116, v46
	v_fmac_f32_e32 v9, v117, v47
	v_fmac_f32_e32 v9, v118, v48
	v_lshl_add_u64 v[10:11], v[6:7], 0, s[0:1]
	s_mov_b32 s0, 0xc000
	v_fmac_f32_e32 v9, v119, v49
	v_add_co_u32_e64 v8, s[0:1], s0, v6
	v_add_f32_e32 v51, 0, v9
	s_nop 0
	v_addc_co_u32_e64 v9, s[0:1], 0, v7, s[0:1]
	s_nop 0
	s_nop 0
	s_mov_b64 s[0:1], 0x12000
	s_waitcnt vmcnt(1)
	v_mul_f32_e32 v10, v129, v32
	v_fmac_f32_e32 v10, v128, v23
	v_fmac_f32_e32 v10, v130, v33
	v_fmac_f32_e32 v10, v131, v45
	s_waitcnt vmcnt(0)
	v_fmac_f32_e32 v10, v132, v46
	v_fmac_f32_e32 v10, v133, v47
	v_fmac_f32_e32 v10, v134, v48
	v_fmac_f32_e32 v10, v135, v49
	v_lshl_add_u64 v[24:25], v[6:7], 0, s[0:1]
	s_mov_b32 s0, 0x12000
	v_add_f32_e32 v52, 0, v10
	v_add_co_u32_e64 v10, s[0:1], s0, v6
	s_nop 1
	v_addc_co_u32_e64 v11, s[0:1], 0, v7, s[0:1]
	s_nop 0
	s_nop 0
	s_nop 0
	s_mov_b64 s[0:1], 0x18000
	s_waitcnt vmcnt(1)
	v_mul_f32_e32 v15, v145, v32
	v_fmac_f32_e32 v15, v144, v23
	v_fmac_f32_e32 v15, v146, v33
	v_fmac_f32_e32 v15, v147, v45
	s_waitcnt vmcnt(0)
	v_fmac_f32_e32 v15, v148, v46
	v_fmac_f32_e32 v15, v149, v47
	v_fmac_f32_e32 v15, v150, v48
	v_lshl_add_u64 v[16:17], v[6:7], 0, s[0:1]
	s_mov_b32 s0, 0x18000
	v_fmac_f32_e32 v15, v151, v49
	v_add_co_u32_e64 v14, s[0:1], s0, v6
	v_add_f32_e32 v53, 0, v15
	s_nop 0
	v_addc_co_u32_e64 v15, s[0:1], 0, v7, s[0:1]
	s_nop 0
	s_waitcnt lgkmcnt(0)
	s_nop 0
	v_lshlrev_b32_e32 v17, 16, v2
	s_mov_b64 s[0:1], 0x6800
	s_waitcnt vmcnt(1)
	v_mul_f32_e32 v16, v161, v32
	v_fmac_f32_e32 v16, v160, v23
	v_fmac_f32_e32 v16, v162, v33
	v_fmac_f32_e32 v16, v163, v45
	s_waitcnt vmcnt(0)
; __device__ __forceinline__ void sw_layers(const Args& a, int l_lo, int l_hi, int wb, int nwb) {
;     ...
;             for (int hseg = 0; hseg < 2; ++hseg) {
;                 const int k0 = hseg * 512 + 8 * lane;
;                 float wf[8]; unpack8(wv[u][hseg], wf);
; #pragma unroll
;                 for (int bb = 0; bb < 5; ++bb) {
;                     const f32x4 s0 = *(const f32x4*)(shp[u] + (size_t)bb * NMODC + k0), s1 = *(const f32x4*)(shp[u] + (size_t)bb * NMODC + k0 + 4);
;                     acc[bb] += s0[0] * wf[0] + s0[1] * wf[1] + s0[2] * wf[2] + s0[3] * wf[3] + s1[0] * wf[4] + s1[1] * wf[5] + s1[2] * wf[6] + s1[3] * wf[7];
;                 }
;             }
; #pragma unroll
;             for (int bb = 0; bb < 5; ++bb) acc[bb] = wave_sum(acc[bb]);
;             if (lane == 0 && okp[u]) {
; #pragma unroll
;                 for (int bb = 0; bb < 5; ++bb) dstp[u][(size_t)bb * ldp[u]] = acc[bb];
;             }
	v_fmac_f32_e32 v16, v164, v46
	v_fmac_f32_e32 v16, v165, v47
	v_fmac_f32_e32 v16, v166, v48
	v_and_b32_e32 v23, 0xffff0000, v2
	v_lshlrev_b32_e32 v32, 16, v3
	v_and_b32_e32 v33, 0xffff0000, v3
	v_lshlrev_b32_e32 v45, 16, v4
	v_and_b32_e32 v46, 0xffff0000, v4
	v_lshlrev_b32_e32 v47, 16, v5
	v_and_b32_e32 v48, 0xffff0000, v5
	s_nop 0
	s_nop 0
	v_fmac_f32_e32 v16, v167, v49
	v_add_f32_e32 v16, 0, v16
	s_waitcnt vmcnt(0)
	v_mul_f32_e32 v25, v105, v23
	v_fmac_f32_e32 v25, v104, v17
	v_fmac_f32_e32 v25, v106, v32
	v_fmac_f32_e32 v25, v107, v33
	v_fmac_f32_e32 v25, v108, v45
	v_fmac_f32_e32 v25, v109, v46
	v_fmac_f32_e32 v25, v110, v47
	v_fmac_f32_e32 v25, v111, v48
	v_add_f32_e32 v2, v50, v25
	v_lshl_add_u64 v[4:5], v[6:7], 0, s[0:1]
	s_nop 0
	s_nop 0
	s_mov_b64 s[0:1], 0xc800
	v_lshl_add_u64 v[12:13], v[6:7], 0, s[0:1]
	s_mov_b64 s[0:1], 0x12800
	s_waitcnt vmcnt(1)
	v_mul_f32_e32 v3, v121, v23
	v_fmac_f32_e32 v3, v120, v17
	v_fmac_f32_e32 v3, v122, v32
	v_fmac_f32_e32 v3, v123, v33
	s_waitcnt vmcnt(0)
	v_fmac_f32_e32 v3, v124, v45
	v_fmac_f32_e32 v3, v125, v46
	v_fmac_f32_e32 v3, v126, v47
	v_fmac_f32_e32 v3, v127, v48
	s_nop 0
	s_nop 0
	v_add_f32_e32 v4, v51, v3
	v_lshl_add_u64 v[12:13], v[6:7], 0, s[0:1]
	s_mov_b64 s[0:1], 0x18800
	s_waitcnt vmcnt(1)
	v_mul_f32_e32 v3, v137, v23
	v_fmac_f32_e32 v3, v136, v17
	v_fmac_f32_e32 v3, v138, v32
	v_fmac_f32_e32 v3, v139, v33
	s_nop 0
	s_nop 0
	s_nop 0
	s_waitcnt vmcnt(2)
	v_fmac_f32_e32 v3, v140, v45
	v_fmac_f32_e32 v3, v141, v46
	v_fmac_f32_e32 v3, v142, v47
	v_fmac_f32_e32 v3, v143, v48
	v_add_f32_e32 v3, v52, v3
	s_waitcnt vmcnt(1)
	v_mul_f32_e32 v5, v153, v23
	v_fmac_f32_e32 v5, v152, v17
	v_fmac_f32_e32 v5, v154, v32
	v_fmac_f32_e32 v5, v155, v33
	v_lshl_add_u64 v[10:11], v[6:7], 0, s[0:1]
	s_nop 0
	s_nop 0
	s_nop 0
	s_waitcnt vmcnt(2)
	v_fmac_f32_e32 v5, v156, v45
	v_fmac_f32_e32 v5, v157, v46
	v_fmac_f32_e32 v5, v158, v47
	v_fmac_f32_e32 v5, v159, v48
	v_add_f32_e32 v5, v53, v5
	s_waitcnt vmcnt(1)
	v_mul_f32_e32 v7, v169, v23
	v_fmac_f32_e32 v7, v168, v17
	v_fmac_f32_e32 v7, v170, v32
	v_fmac_f32_e32 v7, v171, v33
	s_waitcnt vmcnt(0)
	v_fmac_f32_e32 v7, v172, v45
	v_fmac_f32_e32 v7, v173, v46
	v_fmac_f32_e32 v7, v174, v47
	v_fmac_f32_e32 v7, v175, v48
	v_add_f32_e32 v6, v16, v7
	ds_bpermute_b32 v7, v39, v2
	ds_bpermute_b32 v8, v39, v4
	ds_bpermute_b32 v9, v39, v3
	ds_bpermute_b32 v10, v39, v5
	ds_bpermute_b32 v11, v39, v6
	s_waitcnt lgkmcnt(4)
	v_add_f32_e32 v2, v2, v7
	s_waitcnt lgkmcnt(3)
	v_add_f32_e32 v4, v4, v8
	s_waitcnt lgkmcnt(2)
	v_add_f32_e32 v3, v3, v9
	s_waitcnt lgkmcnt(1)
	v_add_f32_e32 v5, v5, v10
	s_waitcnt lgkmcnt(0)
	v_add_f32_e32 v6, v6, v11
	ds_bpermute_b32 v7, v40, v2
	ds_bpermute_b32 v8, v40, v4
	ds_bpermute_b32 v9, v40, v3
	ds_bpermute_b32 v10, v40, v5
	ds_bpermute_b32 v11, v40, v6
	s_waitcnt lgkmcnt(4)
	v_add_f32_e32 v2, v2, v7
	s_waitcnt lgkmcnt(3)
	v_add_f32_e32 v4, v4, v8
	s_waitcnt lgkmcnt(2)
	v_add_f32_e32 v3, v3, v9
	s_waitcnt lgkmcnt(1)
	v_add_f32_e32 v5, v5, v10
	s_waitcnt lgkmcnt(0)
	v_add_f32_e32 v6, v6, v11
	ds_bpermute_b32 v7, v41, v2
	ds_bpermute_b32 v8, v41, v4
	ds_bpermute_b32 v9, v41, v3
	ds_bpermute_b32 v10, v41, v5
	ds_bpermute_b32 v11, v41, v6
	s_waitcnt lgkmcnt(4)
	v_add_f32_e32 v2, v2, v7
	s_waitcnt lgkmcnt(3)
	v_add_f32_e32 v4, v4, v8
	s_waitcnt lgkmcnt(2)
	v_add_f32_e32 v3, v3, v9
	s_waitcnt lgkmcnt(1)
	v_add_f32_e32 v5, v5, v10
	s_waitcnt lgkmcnt(0)
	v_add_f32_e32 v6, v6, v11
	ds_bpermute_b32 v7, v42, v2
	ds_bpermute_b32 v8, v42, v4
	ds_bpermute_b32 v9, v42, v3
	ds_bpermute_b32 v10, v42, v5
	ds_bpermute_b32 v11, v42, v6
	s_waitcnt lgkmcnt(4)
	v_add_f32_e32 v2, v2, v7
	s_waitcnt lgkmcnt(3)
	v_add_f32_e32 v4, v4, v8
	s_waitcnt lgkmcnt(2)
	v_add_f32_e32 v3, v3, v9
	s_waitcnt lgkmcnt(1)
	v_add_f32_e32 v5, v5, v10
	s_waitcnt lgkmcnt(0)
	v_add_f32_e32 v6, v6, v11
	ds_bpermute_b32 v7, v43, v2
	ds_bpermute_b32 v8, v43, v4
	ds_bpermute_b32 v9, v43, v3
	ds_bpermute_b32 v10, v43, v5
	ds_bpermute_b32 v11, v43, v6
	s_waitcnt lgkmcnt(4)
	v_add_f32_e32 v2, v2, v7
	s_waitcnt lgkmcnt(3)
	v_add_f32_e32 v4, v4, v8
	s_waitcnt lgkmcnt(2)
	v_add_f32_e32 v3, v3, v9
	s_waitcnt lgkmcnt(1)
	v_add_f32_e32 v5, v5, v10
	s_waitcnt lgkmcnt(0)
	v_add_f32_e32 v6, v6, v11
	ds_bpermute_b32 v7, v44, v2
	ds_bpermute_b32 v8, v44, v4
	ds_bpermute_b32 v9, v44, v3
	ds_bpermute_b32 v10, v44, v5
	ds_bpermute_b32 v11, v44, v6
	s_and_saveexec_b64 s[0:1], s[38:39]
	s_cbranch_execz .LBB0_85
	s_waitcnt lgkmcnt(4)
	v_add_f32_e32 v2, v2, v7
	v_lshlrev_b32_e32 v206, 2, v22
	s_waitcnt lgkmcnt(2)
	v_add_f32_e32 v9, v3, v9
	v_add_f32_e32 v4, v4, v8
	global_store_dword v[20:21], v2, off
	v_lshl_add_u64 v[2:3], v[20:21], 0, v[206:207]
	global_store_dword v[2:3], v4, off
	v_lshl_add_u64 v[2:3], v[2:3], 0, v[206:207]
	s_waitcnt lgkmcnt(1)
	v_add_f32_e32 v5, v5, v10
	global_store_dword v[2:3], v9, off
	v_lshl_add_u64 v[2:3], v[2:3], 0, v[206:207]
	s_waitcnt lgkmcnt(0)
	v_add_f32_e32 v6, v6, v11
	global_store_dword v[2:3], v5, off
	v_lshl_add_u64 v[2:3], v[2:3], 0, v[206:207]
	global_store_dword v[2:3], v6, off
	s_branch .LBB0_85
